# LP1 + mixer pool GEMM rewritten: weight fragments double-buffered two groups ahead (counted vmcnt) instead of 8 serialized load-wait-MFMA groups
# baseline (speedup 1.0000x reference)
; #define LAS __attribute__((address_space(3)))
; __device__ __forceinline__ unsigned pk2(float lo, float hi) { f32x2 v = {lo, hi}; bf16x2_t b = __builtin_convertvector(v, bf16x2_t); return __builtin_bit_cast(unsigned, b); }
; #define GAS __attribute__((address_space(1)))
; __device__ __forceinline__ void mixer_unit(const Params& p, int layer, int cu, LAS unsigned char* L, int wv) {
;     ...
;     {
;         const int g = wave >> 1, th = wave & 1;
;         bf16x8 dfr[2][4];
; #pragma unroll
;         for (int tb = 0; tb < 2; ++tb)
; #pragma unroll
;             for (int ks = 0; ks < 4; ++ks) dfr[tb][ks] = *(const LAS bf16x8*)(L + ((32 * th + 16 * tb + q16) * DROW + 128 * g + 32 * ks + 8 * quad) * 2);
;         const bf16_t* wp = (const bf16_t*)(PWS + WS_W + (size_t)layer * WL_STRIDE + WL_POOL) + (size_t)g * 128 * 128;
;         u32x2 res[8][2];
; #pragma unroll
;         for (int nt = 0; nt < 8; ++nt) {
;             bf16x8 wf[4];
; #pragma unroll
;             for (int ks = 0; ks < 4; ++ks) wf[ks] = *(const GAS bf16x8*)((const GAS bf16_t*)wp + (16 * nt + q16) * 128 + 32 * ks + 8 * quad);
; #pragma unroll
;             for (int tb = 0; tb < 2; ++tb) {
;                 f32x4 o = (f32x4){0.f, 0.f, 0.f, 0.f};
; #pragma unroll
;                 for (int ks = 0; ks < 4; ++ks) o = __builtin_amdgcn_mfma_f32_16x16x32_bf16(wf[ks], dfr[tb][ks], o, 0, 0, 0);
;                 res[nt][tb].x = pk2(o[0], o[1]); res[nt][tb].y = pk2(o[2], o[3]);
;             }
;             if ((nt & 3) == 3) asm volatile("" ::: "memory");
;         }
.LBB0_1318:
	s_or_b64 exec, exec, s[4:5]
	s_and_b32 s4, s66, 0x7fffff80
	v_lshl_or_b32 v82, s9, 5, v179
	v_or_b32_e32 v0, s4, v180
	s_movk_i32 s4, 0x208
	v_mad_u32_u24 v0, v82, s4, v0
	v_lshl_add_u32 v0, v0, 1, 0
	s_waitcnt lgkmcnt(0)
	s_barrier
	ds_read_b128 v[40:43], v0
	ds_read_b128 v[36:39], v0 offset:64
	ds_read_b128 v[28:31], v0 offset:128
	ds_read_b128 v[8:11], v0 offset:192
	ds_read_b128 v[12:15], v0 offset:16640
	ds_read_b128 v[16:19], v0 offset:16704
	ds_read_b128 v[20:23], v0 offset:16768
	ds_read_b128 v[24:27], v0 offset:16832
	v_mov_b32_e32 v0, v161
	v_readlane_b32 s6, v250, 0
	v_add_u32_e32 v0, 0, v0
	v_add_u32_e32 v0, 0x201c0, v0
	s_nop 0
	s_mul_i32 s6, s6, 0x2900000
	v_lshlrev_b32_e32 v160, 1, v180
	v_mov_b32_e32 v113, v161
	s_waitcnt lgkmcnt(0)
	v_readlane_b32 s5, v251, 48
	v_readlane_b32 s4, v251, 49
	s_add_u32 s6, s5, s6
	s_addc_u32 s7, s4, 0
	s_ashr_i32 s9, s8, 31
	s_lshl_b64 s[4:5], s[8:9], 15
	s_add_u32 s4, s6, s4
	s_addc_u32 s5, s7, s5
	v_lshl_add_u64 v[0:1], s[4:5], 0, v[160:161]
	v_lshlrev_b32_e32 v160, 8, v179
	v_lshl_add_u64 v[80:81], v[0:1], 0, v[160:161]
	s_mov_b64 s[4:5], 0x2800000
	v_lshl_add_u64 v[244:245], v[80:81], 0, s[4:5]
	global_load_dwordx4 v[212:215], v[244:245], off
	global_load_dwordx4 v[216:219], v[244:245], off offset:64
	global_load_dwordx4 v[220:223], v[244:245], off offset:128
	global_load_dwordx4 v[224:227], v[244:245], off offset:192
	v_add_co_u32_e32 v244, vcc, 0x1000, v244
	s_nop 1
	v_addc_co_u32_e32 v245, vcc, 0, v245, vcc
	global_load_dwordx4 v[228:231], v[244:245], off
	global_load_dwordx4 v[232:235], v[244:245], off offset:64
	global_load_dwordx4 v[236:239], v[244:245], off offset:128
	global_load_dwordx4 v[240:243], v[244:245], off offset:192
	v_add_co_u32_e32 v244, vcc, 0x1000, v244
	s_nop 1
	v_addc_co_u32_e32 v245, vcc, 0, v245, vcc
	s_add_i32 s65, s65, s20
	v_add_u32_e32 v2, s67, v82
	v_ashrrev_i32_e32 v3, 31, v2
	v_lshlrev_b64 v[6:7], 11, v[2:3]
	v_lshl_add_u64 v[6:7], s[12:13], 0, v[6:7]
	s_and_b32 s4, s66, 0xffffff80
	s_ashr_i32 s5, s4, 31
	s_lshl_b64 s[4:5], s[4:5], 1
	v_lshl_add_u64 v[6:7], v[6:7], 0, s[4:5]
	v_lshl_add_u64 v[6:7], v[6:7], 0, v[112:113]
	v_add_u32_e32 v0, 16, v2
	v_ashrrev_i32_e32 v1, 31, v0
	v_lshlrev_b64 v[0:1], 11, v[0:1]
	v_lshl_add_u64 v[0:1], s[12:13], 0, v[0:1]
	v_lshl_add_u64 v[0:1], v[0:1], 0, s[4:5]
	v_lshl_add_u64 v[0:1], v[0:1], 0, v[112:113]
	s_waitcnt vmcnt(7)
	v_mfma_f32_16x16x32_bf16 v[152:155], v[212:215], v[40:43], 0
	v_mfma_f32_16x16x32_bf16 v[156:159], v[212:215], v[12:15], 0
	s_waitcnt vmcnt(6)
	v_mfma_f32_16x16x32_bf16 v[152:155], v[216:219], v[36:39], v[152:155]
	v_mfma_f32_16x16x32_bf16 v[156:159], v[216:219], v[16:19], v[156:159]
	s_waitcnt vmcnt(5)
	v_mfma_f32_16x16x32_bf16 v[152:155], v[220:223], v[28:31], v[152:155]
	v_mfma_f32_16x16x32_bf16 v[156:159], v[220:223], v[20:23], v[156:159]
	s_waitcnt vmcnt(4)
	v_mfma_f32_16x16x32_bf16 v[152:155], v[224:227], v[8:11], v[152:155]
	v_mfma_f32_16x16x32_bf16 v[156:159], v[224:227], v[24:27], v[156:159]
	global_load_dwordx4 v[212:215], v[244:245], off
	global_load_dwordx4 v[216:219], v[244:245], off offset:64
	global_load_dwordx4 v[220:223], v[244:245], off offset:128
	global_load_dwordx4 v[224:227], v[244:245], off offset:192
	v_add_co_u32_e32 v244, vcc, 0x1000, v244
	s_nop 1
	v_addc_co_u32_e32 v245, vcc, 0, v245, vcc
	s_waitcnt vmcnt(7)
	v_mfma_f32_16x16x32_bf16 v[162:165], v[228:231], v[40:43], 0
	v_mfma_f32_16x16x32_bf16 v[166:169], v[228:231], v[12:15], 0
	s_waitcnt vmcnt(6)
	v_mfma_f32_16x16x32_bf16 v[162:165], v[232:235], v[36:39], v[162:165]
	v_mfma_f32_16x16x32_bf16 v[166:169], v[232:235], v[16:19], v[166:169]
	s_nop 5
	v_cvt_pk_bf16_f32 v114, v152, v153
	v_cvt_pk_bf16_f32 v115, v154, v155
	v_cvt_pk_bf16_f32 v116, v156, v157
	v_cvt_pk_bf16_f32 v117, v158, v159
	s_waitcnt vmcnt(5)
	v_mfma_f32_16x16x32_bf16 v[162:165], v[236:239], v[28:31], v[162:165]
	v_mfma_f32_16x16x32_bf16 v[166:169], v[236:239], v[20:23], v[166:169]
	s_waitcnt vmcnt(4)
	v_mfma_f32_16x16x32_bf16 v[162:165], v[240:243], v[8:11], v[162:165]
	v_mfma_f32_16x16x32_bf16 v[166:169], v[240:243], v[24:27], v[166:169]
	global_load_dwordx4 v[228:231], v[244:245], off
	global_load_dwordx4 v[232:235], v[244:245], off offset:64
	global_load_dwordx4 v[236:239], v[244:245], off offset:128
	global_load_dwordx4 v[240:243], v[244:245], off offset:192
	v_add_co_u32_e32 v244, vcc, 0x1000, v244
	s_nop 1
	v_addc_co_u32_e32 v245, vcc, 0, v245, vcc
	s_waitcnt vmcnt(7)
	v_mfma_f32_16x16x32_bf16 v[152:155], v[212:215], v[40:43], 0
	v_mfma_f32_16x16x32_bf16 v[156:159], v[212:215], v[12:15], 0
	s_waitcnt vmcnt(6)
	v_mfma_f32_16x16x32_bf16 v[152:155], v[216:219], v[36:39], v[152:155]
	v_mfma_f32_16x16x32_bf16 v[156:159], v[216:219], v[16:19], v[156:159]
	s_nop 5
	v_cvt_pk_bf16_f32 v118, v162, v163
	v_cvt_pk_bf16_f32 v119, v164, v165
	v_cvt_pk_bf16_f32 v120, v166, v167
	v_cvt_pk_bf16_f32 v121, v168, v169
	s_waitcnt vmcnt(5)
	v_mfma_f32_16x16x32_bf16 v[152:155], v[220:223], v[28:31], v[152:155]
	v_mfma_f32_16x16x32_bf16 v[156:159], v[220:223], v[20:23], v[156:159]
	s_waitcnt vmcnt(4)
	v_mfma_f32_16x16x32_bf16 v[152:155], v[224:227], v[8:11], v[152:155]
	v_mfma_f32_16x16x32_bf16 v[156:159], v[224:227], v[24:27], v[156:159]
	global_load_dwordx4 v[212:215], v[244:245], off
	global_load_dwordx4 v[216:219], v[244:245], off offset:64
	global_load_dwordx4 v[220:223], v[244:245], off offset:128
	global_load_dwordx4 v[224:227], v[244:245], off offset:192
	v_add_co_u32_e32 v244, vcc, 0x1000, v244
	s_nop 1
	v_addc_co_u32_e32 v245, vcc, 0, v245, vcc
	s_waitcnt vmcnt(7)
	v_mfma_f32_16x16x32_bf16 v[162:165], v[228:231], v[40:43], 0
	v_mfma_f32_16x16x32_bf16 v[166:169], v[228:231], v[12:15], 0
	s_waitcnt vmcnt(6)
; __device__ __forceinline__ unsigned pk2(float lo, float hi) { f32x2 v = {lo, hi}; bf16x2_t b = __builtin_convertvector(v, bf16x2_t); return __builtin_bit_cast(unsigned, b); }
; #define GAS __attribute__((address_space(1)))
; __device__ __forceinline__ void mixer_unit(const Params& p, int layer, int cu, LAS unsigned char* L, int wv) {
;     ...
;         for (int nt = 0; nt < 8; ++nt) {
;             bf16x8 wf[4];
; #pragma unroll
;             for (int ks = 0; ks < 4; ++ks) wf[ks] = *(const GAS bf16x8*)((const GAS bf16_t*)wp + (16 * nt + q16) * 128 + 32 * ks + 8 * quad);
; #pragma unroll
;             for (int tb = 0; tb < 2; ++tb) {
;                 f32x4 o = (f32x4){0.f, 0.f, 0.f, 0.f};
; #pragma unroll
;                 for (int ks = 0; ks < 4; ++ks) o = __builtin_amdgcn_mfma_f32_16x16x32_bf16(wf[ks], dfr[tb][ks], o, 0, 0, 0);
;                 res[nt][tb].x = pk2(o[0], o[1]); res[nt][tb].y = pk2(o[2], o[3]);
;             }
;             if ((nt & 3) == 3) asm volatile("" ::: "memory");
;         }
; #pragma unroll
;         for (int nt = 0; nt < 8; ++nt)
; #pragma unroll
;             for (int tb = 0; tb < 2; ++tb) *(GAS u32x2*)((GAS bf16_t*)mix + (size_t)(tok0 + 32 * th + 16 * tb + q16) * DM + 512 + 128 * g + 16 * nt + 4 * quad) = res[nt][tb];
	v_mfma_f32_16x16x32_bf16 v[162:165], v[232:235], v[36:39], v[162:165]
	v_mfma_f32_16x16x32_bf16 v[166:169], v[232:235], v[16:19], v[166:169]
	s_nop 5
	v_cvt_pk_bf16_f32 v122, v152, v153
	v_cvt_pk_bf16_f32 v123, v154, v155
	v_cvt_pk_bf16_f32 v124, v156, v157
	v_cvt_pk_bf16_f32 v125, v158, v159
	s_waitcnt vmcnt(5)
	v_mfma_f32_16x16x32_bf16 v[162:165], v[236:239], v[28:31], v[162:165]
	v_mfma_f32_16x16x32_bf16 v[166:169], v[236:239], v[20:23], v[166:169]
	s_waitcnt vmcnt(4)
	v_mfma_f32_16x16x32_bf16 v[162:165], v[240:243], v[8:11], v[162:165]
	v_mfma_f32_16x16x32_bf16 v[166:169], v[240:243], v[24:27], v[166:169]
	global_load_dwordx4 v[228:231], v[244:245], off
	global_load_dwordx4 v[232:235], v[244:245], off offset:64
	global_load_dwordx4 v[236:239], v[244:245], off offset:128
	global_load_dwordx4 v[240:243], v[244:245], off offset:192
	v_add_co_u32_e32 v244, vcc, 0x1000, v244
	s_nop 1
	v_addc_co_u32_e32 v245, vcc, 0, v245, vcc
	s_waitcnt vmcnt(7)
	v_mfma_f32_16x16x32_bf16 v[152:155], v[212:215], v[40:43], 0
	v_mfma_f32_16x16x32_bf16 v[156:159], v[212:215], v[12:15], 0
	s_waitcnt vmcnt(6)
	v_mfma_f32_16x16x32_bf16 v[152:155], v[216:219], v[36:39], v[152:155]
	v_mfma_f32_16x16x32_bf16 v[156:159], v[216:219], v[16:19], v[156:159]
	s_nop 5
	v_cvt_pk_bf16_f32 v126, v162, v163
	v_cvt_pk_bf16_f32 v127, v164, v165
	v_cvt_pk_bf16_f32 v128, v166, v167
	v_cvt_pk_bf16_f32 v129, v168, v169
	s_waitcnt vmcnt(5)
	v_mfma_f32_16x16x32_bf16 v[152:155], v[220:223], v[28:31], v[152:155]
	v_mfma_f32_16x16x32_bf16 v[156:159], v[220:223], v[20:23], v[156:159]
	s_waitcnt vmcnt(4)
	v_mfma_f32_16x16x32_bf16 v[152:155], v[224:227], v[8:11], v[152:155]
	v_mfma_f32_16x16x32_bf16 v[156:159], v[224:227], v[24:27], v[156:159]
	global_load_dwordx4 v[212:215], v[244:245], off
	global_load_dwordx4 v[216:219], v[244:245], off offset:64
	global_load_dwordx4 v[220:223], v[244:245], off offset:128
	global_load_dwordx4 v[224:227], v[244:245], off offset:192
	v_add_co_u32_e32 v244, vcc, 0x1000, v244
	s_nop 1
	v_addc_co_u32_e32 v245, vcc, 0, v245, vcc
	s_waitcnt vmcnt(7)
	v_mfma_f32_16x16x32_bf16 v[162:165], v[228:231], v[40:43], 0
	v_mfma_f32_16x16x32_bf16 v[166:169], v[228:231], v[12:15], 0
	s_waitcnt vmcnt(6)
	v_mfma_f32_16x16x32_bf16 v[162:165], v[232:235], v[36:39], v[162:165]
	v_mfma_f32_16x16x32_bf16 v[166:169], v[232:235], v[16:19], v[166:169]
	s_nop 5
	v_cvt_pk_bf16_f32 v130, v152, v153
	v_cvt_pk_bf16_f32 v131, v154, v155
	v_cvt_pk_bf16_f32 v132, v156, v157
	v_cvt_pk_bf16_f32 v133, v158, v159
	s_waitcnt vmcnt(5)
	v_mfma_f32_16x16x32_bf16 v[162:165], v[236:239], v[28:31], v[162:165]
	v_mfma_f32_16x16x32_bf16 v[166:169], v[236:239], v[20:23], v[166:169]
	s_waitcnt vmcnt(4)
	v_mfma_f32_16x16x32_bf16 v[162:165], v[240:243], v[8:11], v[162:165]
	v_mfma_f32_16x16x32_bf16 v[166:169], v[240:243], v[24:27], v[166:169]
	global_load_dwordx4 v[228:231], v[244:245], off
	global_load_dwordx4 v[232:235], v[244:245], off offset:64
	global_load_dwordx4 v[236:239], v[244:245], off offset:128
	global_load_dwordx4 v[240:243], v[244:245], off offset:192
	v_add_co_u32_e32 v244, vcc, 0x1000, v244
	s_nop 1
	v_addc_co_u32_e32 v245, vcc, 0, v245, vcc
	s_waitcnt vmcnt(7)
	v_mfma_f32_16x16x32_bf16 v[152:155], v[212:215], v[40:43], 0
	v_mfma_f32_16x16x32_bf16 v[156:159], v[212:215], v[12:15], 0
	s_waitcnt vmcnt(6)
	v_mfma_f32_16x16x32_bf16 v[152:155], v[216:219], v[36:39], v[152:155]
	v_mfma_f32_16x16x32_bf16 v[156:159], v[216:219], v[16:19], v[156:159]
	s_nop 5
	v_cvt_pk_bf16_f32 v134, v162, v163
	v_cvt_pk_bf16_f32 v135, v164, v165
	v_cvt_pk_bf16_f32 v136, v166, v167
	v_cvt_pk_bf16_f32 v137, v168, v169
	s_waitcnt vmcnt(5)
	v_mfma_f32_16x16x32_bf16 v[152:155], v[220:223], v[28:31], v[152:155]
	v_mfma_f32_16x16x32_bf16 v[156:159], v[220:223], v[20:23], v[156:159]
	s_waitcnt vmcnt(4)
	v_mfma_f32_16x16x32_bf16 v[152:155], v[224:227], v[8:11], v[152:155]
	v_mfma_f32_16x16x32_bf16 v[156:159], v[224:227], v[24:27], v[156:159]
	s_waitcnt vmcnt(3)
	v_mfma_f32_16x16x32_bf16 v[162:165], v[228:231], v[40:43], 0
	v_mfma_f32_16x16x32_bf16 v[166:169], v[228:231], v[12:15], 0
	s_waitcnt vmcnt(2)
	v_mfma_f32_16x16x32_bf16 v[162:165], v[232:235], v[36:39], v[162:165]
	v_mfma_f32_16x16x32_bf16 v[166:169], v[232:235], v[16:19], v[166:169]
	s_nop 5
	v_cvt_pk_bf16_f32 v138, v152, v153
	v_cvt_pk_bf16_f32 v139, v154, v155
	v_cvt_pk_bf16_f32 v140, v156, v157
	v_cvt_pk_bf16_f32 v141, v158, v159
	s_waitcnt vmcnt(1)
	v_mfma_f32_16x16x32_bf16 v[162:165], v[236:239], v[28:31], v[162:165]
	v_mfma_f32_16x16x32_bf16 v[166:169], v[236:239], v[20:23], v[166:169]
	s_waitcnt vmcnt(0)
	v_mfma_f32_16x16x32_bf16 v[162:165], v[240:243], v[8:11], v[162:165]
	v_mfma_f32_16x16x32_bf16 v[166:169], v[240:243], v[24:27], v[166:169]
	s_nop 7
	s_nop 7
	v_cvt_pk_bf16_f32 v142, v162, v163
	v_cvt_pk_bf16_f32 v143, v164, v165
	v_cvt_pk_bf16_f32 v144, v166, v167
	v_cvt_pk_bf16_f32 v145, v168, v169
	s_cmpk_gt_i32 s65, 0x41f
	global_store_dwordx2 v[6:7], v[114:115], off offset:1024
	global_store_dwordx2 v[0:1], v[116:117], off offset:1024
	global_store_dwordx2 v[6:7], v[118:119], off offset:1056
	global_store_dwordx2 v[0:1], v[120:121], off offset:1056
	global_store_dwordx2 v[6:7], v[122:123], off offset:1088
	global_store_dwordx2 v[0:1], v[124:125], off offset:1088
	global_store_dwordx2 v[6:7], v[126:127], off offset:1120
	global_store_dwordx2 v[0:1], v[128:129], off offset:1120
	global_store_dwordx2 v[6:7], v[130:131], off offset:1152
	global_store_dwordx2 v[0:1], v[132:133], off offset:1152
	global_store_dwordx2 v[6:7], v[134:135], off offset:1184
	global_store_dwordx2 v[0:1], v[136:137], off offset:1184
	global_store_dwordx2 v[6:7], v[138:139], off offset:1216
	global_store_dwordx2 v[0:1], v[140:141], off offset:1216
	global_store_dwordx2 v[6:7], v[142:143], off offset:1248
	global_store_dwordx2 v[0:1], v[144:145], off offset:1248
	s_barrier
	s_cbranch_scc1 .LBB0_1801
